# balanced attention item pairing, variant that permutes only the two middle sequence quarters (heaviest and lightest items stay as in the baseline)
# baseline (speedup 1.0000x reference)
.LBB0_1073:
	v_readlane_b32 s98, v252, 49
	s_mov_b32 s100, 0x76543210
	s_mov_b32 s101, 0xfedcba98
	s_cmp_eq_u32 s93, 1
	s_cselect_b32 s100, 0x30f49d6e, s100
	s_cselect_b32 s101, 0xb7218ca5, s101
	s_cmp_eq_u32 s93, 2
	s_cselect_b32 s100, 0x50f26a18, s100
	s_cselect_b32 s101, 0xd943bec7, s101
	s_cmp_eq_u32 s93, 3
	s_cselect_b32 s100, 0x76543210, s100
	s_cselect_b32 s101, 0xfedcba98, s101
	s_lshr_b32 s98, s98, 1
	s_lshl_b32 s98, s98, 2
	s_lshr_b64 s[100:101], s[100:101], s98
	s_and_b32 s100, s100, 15
	s_sub_i32 s101, 15, s100
	s_lshl_b32 s0, s93, 4
	s_bitcmp0_b32 s93, 0
	v_readlane_b32 s1, v252, 49
	v_readlane_b32 s2, v253, 2
	s_cselect_b32 s100, s100, s101
	s_cselect_b32 s1, s1, s2
	s_add_i32 s0, s0, s100
	v_mov_b32 v37, v178
	s_sub_i32 s68, 63, s0
	v_ashrrev_i32_e32 v225, 6, v37
	v_lshlrev_b32_e32 v207, 3, v225
	v_bfe_u32 v208, v37, 2, 3
	s_lshl_b32 s33, s68, 6
	v_or_b32_e32 v226, v207, v208
	v_add_u32_e32 v184, s33, v226
	v_ashrrev_i32_e32 v185, 31, v184
	s_and_b32 s2, s1, 1
	v_and_b32_e32 v36, 3, v37
	v_lshl_add_u64 v[34:35], v[184:185], 0, s[70:71]
	s_nop 0
	v_lshlrev_b64 v[2:3], 10, v[34:35]
	v_readlane_b32 s18, v252, 5
	v_readlane_b32 s19, v252, 6
	v_lshl_or_b32 v42, s2, 2, v36
	v_bfe_u32 v199, v37, 5, 1
	v_lshl_add_u64 v[2:3], s[18:19], 0, v[2:3]
	v_lshlrev_b32_e32 v0, 7, v42
	v_lshl_add_u64 v[2:3], v[2:3], 0, v[0:1]
	v_lshlrev_b32_e32 v0, 4, v199
	v_lshl_add_u64 v[2:3], v[2:3], 0, v[0:1]
	s_movk_i32 s3, 0x60
	s_mov_b32 s74, s0
	global_load_dwordx4 v[162:165], v[2:3], off
	global_load_dwordx4 v[166:169], v[2:3], off offset:32
	global_load_dwordx4 v[170:173], v[2:3], off offset:64
	global_load_dwordx4 v[174:177], v[2:3], off offset:96
	v_mad_u64_u32 v[2:3], s[0:1], v34, s3, v[180:181]
	s_nop 7
	s_nop 4
	v_mad_i32_i24 v3, v35, s3, v3
	s_lshl_b32 s72, s2, 4
	v_lshl_add_u64 v[2:3], v[2:3], 0, s[72:73]
	v_lshlrev_b32_e32 v0, 2, v36
	s_nop 0
	s_or_b32 s20, s2, s65
	v_lshl_add_u64 v[2:3], v[2:3], 0, v[0:1]
	s_nop 1
	v_readlane_b32 s14, v252, 17
	v_readlane_b32 s15, v252, 18
	global_load_dword v0, v[2:3], off
	global_load_dword v223, v[2:3], off offset:32
	global_load_dword v185, v[2:3], off offset:64
	s_lshl_b32 s2, s20, 15
	s_mov_b64 s[10:11], s[14:15]
	v_lshrrev_b32_e32 v3, 4, v37
	s_nop 1
	v_readlane_b32 s16, v252, 19
	v_readlane_b32 s17, v252, 20
	s_add_u32 s0, s10, s2
	v_lshlrev_b32_e32 v38, 3, v37
	v_xor_b32_e32 v3, v3, v37
	v_readlane_b32 s18, v252, 21
	v_readlane_b32 s19, v252, 22
	s_mov_b64 s[12:13], s[16:17]
	s_addc_u32 s1, s11, 0
	v_and_b32_e32 v2, 0xffffffc0, v38
	v_lshlrev_b32_e32 v3, 3, v3
	s_add_u32 s2, s12, s2
	v_and_or_b32 v186, v3, 56, v2
	v_lshlrev_b32_e32 v224, 4, v37
	s_mov_b32 s4, 0x1ffffffc
	s_addc_u32 s3, s13, 0
	s_ashr_i32 s72, s68, 4
	v_and_b32_e32 v2, 0xfc0, v224
	v_and_or_b32 v3, v225, s4, v36
	v_ashrrev_i32_e32 v187, 31, v186
	v_lshl_add_u32 v188, v3, 3, v2
	v_lshl_add_u64 v[2:3], v[186:187], 1, s[0:1]
	s_min_i32 s0, s72, 0
	v_ashrrev_i32_e32 v189, 31, v188
	s_ashr_i32 s1, s0, 31
	v_add_u32_e32 v200, 0, v224
	s_nop 0
	v_readfirstlane_b32 s99, v200
	v_lshl_add_u64 v[4:5], v[188:189], 1, s[2:3]
	s_lshl_b64 s[0:1], s[0:1], 13
	v_readfirstlane_b32 s2, v200
	v_lshl_add_u64 v[6:7], v[2:3], 0, s[0:1]
	s_mov_b32 m0, s2
	v_add_u32_e32 v213, 0x2000, v200
	global_load_lds_dwordx4 v[6:7], off
	v_lshl_add_u64 v[6:7], v[4:5], 0, s[0:1]
	v_readfirstlane_b32 s0, v213
	s_mov_b32 m0, s0
	s_min_i32 s0, s72, 1
	s_ashr_i32 s1, s0, 31
	v_add_u32_e32 v214, 0x4000, v200
	s_lshl_b64 s[0:1], s[0:1], 13
	v_readfirstlane_b32 s2, v214
	global_load_lds_dwordx4 v[6:7], off
	v_lshl_add_u64 v[6:7], v[2:3], 0, s[0:1]
	s_mov_b32 m0, s2
	v_add_u32_e32 v215, 0x6000, v200
	global_load_lds_dwordx4 v[6:7], off
	v_lshl_add_u64 v[6:7], v[4:5], 0, s[0:1]
	v_readfirstlane_b32 s0, v215
	s_mov_b32 m0, s0
	s_min_i32 s0, s72, 2
	s_ashr_i32 s1, s0, 31
	v_add_u32_e32 v216, 0x8000, v200
	s_lshl_b64 s[0:1], s[0:1], 13
	v_readfirstlane_b32 s2, v216
	global_load_lds_dwordx4 v[6:7], off
	v_lshl_add_u64 v[6:7], v[2:3], 0, s[0:1]
	s_mov_b32 m0, s2
	v_add_u32_e32 v217, 0xa000, v200
	global_load_lds_dwordx4 v[6:7], off
	v_lshl_add_u64 v[6:7], v[4:5], 0, s[0:1]
	v_readfirstlane_b32 s0, v217
	s_mov_b32 m0, s0
	s_min_i32 s0, s72, 3
	s_ashr_i32 s1, s0, 31
	v_add_u32_e32 v218, 0xc000, v200
	s_lshl_b64 s[0:1], s[0:1], 13
	v_readfirstlane_b32 s2, v218
	global_load_lds_dwordx4 v[6:7], off
	v_lshl_add_u64 v[2:3], v[2:3], 0, s[0:1]
	s_mov_b32 m0, s2
	v_add_u32_e32 v221, 0xe000, v200
	global_load_lds_dwordx4 v[2:3], off
	v_lshl_add_u64 v[2:3], v[4:5], 0, s[0:1]
	v_readfirstlane_b32 s0, v221
	s_mov_b32 m0, s0
	s_sub_i32 s0, s33, 31
	global_load_lds_dwordx4 v[2:3], off
	v_subrev_u32_e32 v2, 31, v184
	v_ashrrev_i32_e32 v40, 4, v2
	v_lshrrev_b32_e32 v2, 5, v37
	v_bfe_u32 v3, v37, 1, 3
	v_bitop3_b32 v2, v2, v3, 1 bitop3:0x6c
	v_lshlrev_b32_e32 v201, 4, v2
	v_bitop3_b32 v2, v199, v3, 2 bitop3:0x36
	v_lshlrev_b32_e32 v202, 4, v2
	v_bitop3_b32 v2, v199, v3, 4 bitop3:0x36
	v_lshlrev_b32_e32 v4, 7, v37
	v_lshlrev_b32_e32 v203, 4, v2
	v_bitop3_b32 v2, v199, v3, 6 bitop3:0x36
	s_ashr_i32 s92, s0, 4
	v_lshlrev_b32_e32 v204, 4, v2
	v_and_b32_e32 v2, 0xf80, v4
	s_waitcnt vmcnt(0)
	v_add_u32_e32 v205, 0, v2
	s_cmp_gt_i32 s72, -1
	s_mov_b32 s64, s20
	v_lshlrev_b32_e32 v210, 2, v199
	s_cselect_b64 s[66:67], -1, 0
	s_cmp_lt_i32 s72, 0
	v_add_u32_e32 v222, v205, v201
	v_add_u32_e32 v219, v205, v202
	v_add_u32_e32 v212, v205, v203
	v_add_u32_e32 v211, v205, v204
	s_nop 2
	v_readlane_b32 s8, v252, 11
	v_readlane_b32 s9, v252, 12
	s_mov_b64 s[14:15], s[18:19]
	s_waitcnt vmcnt(0) lgkmcnt(0)
	s_barrier
	s_cbranch_scc1 .LBB0_1077
	ds_read_b128 v[2:5], v222
	ds_read_b128 v[6:9], v222 offset:4096
	ds_read_b128 v[44:47], v219
	ds_read_b128 v[48:51], v219 offset:4096
	s_cmp_gt_i32 s92, 62
	s_waitcnt lgkmcnt(3)
	v_mfma_f32_32x32x16_bf16 v[18:33], v[2:5], v[162:165], 0
	s_waitcnt lgkmcnt(2)
	v_mfma_f32_32x32x16_bf16 v[2:17], v[6:9], v[162:165], 0
	s_waitcnt lgkmcnt(1)
	v_mfma_f32_32x32x16_bf16 v[18:33], v[44:47], v[166:169], v[18:33]
	s_waitcnt lgkmcnt(0)
	v_mfma_f32_32x32x16_bf16 v[2:17], v[48:51], v[166:169], v[2:17]
	ds_read_b128 v[44:47], v212
	ds_read_b128 v[48:51], v212 offset:4096
	s_waitcnt lgkmcnt(1)
	v_mfma_f32_32x32x16_bf16 v[18:33], v[44:47], v[170:173], v[18:33]
	s_waitcnt lgkmcnt(0)
	v_mfma_f32_32x32x16_bf16 v[2:17], v[48:51], v[170:173], v[2:17]
	ds_read_b128 v[44:47], v211
	ds_read_b128 v[48:51], v211 offset:4096
	s_waitcnt lgkmcnt(1)
	v_mfma_f32_32x32x16_bf16 v[18:33], v[44:47], v[174:177], v[18:33]
	s_waitcnt lgkmcnt(0)
	v_mfma_f32_32x32x16_bf16 v[2:17], v[48:51], v[174:177], v[2:17]
	s_cbranch_scc1 .LBB0_1076
	v_sub_u32_e32 v39, v40, v210
	v_cmp_gt_i32_e64 s[58:59], 26, v39
	v_cmp_gt_i32_e64 s[62:63], 27, v39
	v_cmp_gt_i32_e64 s[56:57], 25, v39
	s_and_b64 s[58:59], s[62:63], s[58:59]
	v_cmp_gt_i32_e64 s[54:55], 24, v39
	s_and_b64 s[56:57], s[58:59], s[56:57]
	v_cmp_gt_i32_e64 s[52:53], 19, v39
	s_and_b64 s[54:55], s[56:57], s[54:55]
	v_cmp_gt_i32_e64 s[50:51], 18, v39
	s_and_b64 s[52:53], s[54:55], s[52:53]
	v_cmp_gt_i32_e64 s[48:49], 17, v39
	s_and_b64 s[50:51], s[52:53], s[50:51]
	v_cmp_gt_i32_e64 s[46:47], 16, v39
	s_and_b64 s[48:49], s[50:51], s[48:49]
	v_cmp_gt_i32_e64 s[44:45], 11, v39
	s_and_b64 s[46:47], s[48:49], s[46:47]
	v_cmp_gt_i32_e64 s[42:43], 10, v39
	s_and_b64 s[44:45], s[46:47], s[44:45]
	v_cmp_gt_i32_e64 s[40:41], 9, v39
	s_and_b64 s[42:43], s[44:45], s[42:43]
	v_cmp_gt_i32_e64 s[38:39], 8, v39
	s_and_b64 s[40:41], s[42:43], s[40:41]
	v_cmp_gt_i32_e64 s[36:37], 3, v39
	s_and_b64 s[38:39], s[40:41], s[38:39]
	v_cmp_gt_i32_e64 s[34:35], 2, v39
	s_and_b64 s[36:37], s[38:39], s[36:37]
	v_cmp_gt_i32_e64 s[30:31], 1, v39
	s_and_b64 s[34:35], s[36:37], s[34:35]
	v_cmp_gt_i32_e64 s[28:29], 0, v39
	s_and_b64 s[30:31], s[34:35], s[30:31]
	s_and_b64 s[28:29], s[30:31], s[28:29]
	v_cmp_gt_i32_e64 s[60:61], 58, v39
	v_cndmask_b32_e64 v18, v18, v196, s[28:29]
	v_cmp_gt_i32_e64 s[28:29], 59, v39
	v_cmp_gt_i32_e64 s[26:27], 57, v39
	v_cmp_gt_i32_e64 s[24:25], 56, v39
	v_cndmask_b32_e64 v17, v17, v196, s[28:29]
	s_and_b64 s[28:29], s[28:29], s[60:61]
	s_and_b64 s[26:27], s[28:29], s[26:27]
	v_cmp_gt_i32_e64 s[22:23], 51, v39
	s_and_b64 s[24:25], s[26:27], s[24:25]
	v_cmp_gt_i32_e64 s[20:21], 50, v39
	s_and_b64 s[22:23], s[24:25], s[22:23]
	v_cmp_gt_i32_e64 s[18:19], 49, v39
	s_and_b64 s[20:21], s[22:23], s[20:21]
	v_cmp_gt_i32_e64 s[16:17], 48, v39
	s_and_b64 s[18:19], s[20:21], s[18:19]
	v_cmp_gt_i32_e64 s[14:15], 43, v39
	s_and_b64 s[16:17], s[18:19], s[16:17]
	v_cmp_gt_i32_e64 s[12:13], 42, v39
	s_and_b64 s[14:15], s[16:17], s[14:15]
	v_cmp_gt_i32_e64 s[8:9], 41, v39
	s_and_b64 s[12:13], s[14:15], s[12:13]
	v_cmp_gt_i32_e64 s[6:7], 40, v39
	s_and_b64 s[8:9], s[12:13], s[8:9]
	v_cmp_gt_i32_e64 s[4:5], 35, v39
	s_and_b64 s[6:7], s[8:9], s[6:7]
	v_cmp_gt_i32_e64 s[2:3], 34, v39
	s_and_b64 s[4:5], s[6:7], s[4:5]
	v_cmp_gt_i32_e64 s[0:1], 33, v39
	s_and_b64 s[2:3], s[4:5], s[2:3]
	v_cmp_gt_i32_e32 vcc, 32, v39
	s_and_b64 s[0:1], s[2:3], s[0:1]
	s_and_b64 vcc, s[0:1], vcc
	v_cndmask_b32_e64 v33, v33, v196, s[62:63]
	v_cndmask_b32_e64 v32, v32, v196, s[58:59]
	v_cndmask_b32_e64 v31, v31, v196, s[56:57]
	v_cndmask_b32_e64 v30, v30, v196, s[54:55]
	v_cndmask_b32_e64 v29, v29, v196, s[52:53]
	v_cndmask_b32_e64 v28, v28, v196, s[50:51]
	v_cndmask_b32_e64 v27, v27, v196, s[48:49]
	v_cndmask_b32_e64 v26, v26, v196, s[46:47]
	v_cndmask_b32_e64 v25, v25, v196, s[44:45]
	v_cndmask_b32_e64 v24, v24, v196, s[42:43]
	v_cndmask_b32_e64 v23, v23, v196, s[40:41]
	v_cndmask_b32_e64 v22, v22, v196, s[38:39]
	v_cndmask_b32_e64 v21, v21, v196, s[36:37]
	v_cndmask_b32_e64 v20, v20, v196, s[34:35]
	v_cndmask_b32_e64 v19, v19, v196, s[30:31]
	v_cndmask_b32_e64 v16, v16, v196, s[28:29]
	v_cndmask_b32_e64 v15, v15, v196, s[26:27]
	v_cndmask_b32_e64 v14, v14, v196, s[24:25]
	v_cndmask_b32_e64 v13, v13, v196, s[22:23]
	v_cndmask_b32_e64 v12, v12, v196, s[20:21]
	v_cndmask_b32_e64 v11, v11, v196, s[18:19]
	v_cndmask_b32_e64 v10, v10, v196, s[16:17]
	v_cndmask_b32_e64 v9, v9, v196, s[14:15]
	v_cndmask_b32_e64 v8, v8, v196, s[12:13]
	v_cndmask_b32_e64 v7, v7, v196, s[8:9]
	v_cndmask_b32_e64 v6, v6, v196, s[6:7]
	v_cndmask_b32_e64 v5, v5, v196, s[4:5]
	v_cndmask_b32_e64 v4, v4, v196, s[2:3]
	v_cndmask_b32_e64 v3, v3, v196, s[0:1]
	v_cndmask_b32_e32 v2, v2, v196, vcc
